# baseline (speedup 1.0000x reference)
; #define SBAR() __builtin_amdgcn_sched_barrier(0)
; __device__ __forceinline__ int crow(int r, int hi) { return (r & 3) + 8 * (r >> 2) + 4 * hi; }
; template <int MODE>
; __device__ __forceinline__ void partialSM(f32x16& p0, f32x16& p1, float& m_reg, float& mn, float& alpha, int rel0, int hi, bool need_mask) {
;     constexpr float SCALE = Cfg<MODE>::SCALE;
;     constexpr float C = SCALE * LOG2E;
;     if (MODE == 1) {
;         if (need_mask) {
; #pragma unroll
;             for (int r = 0; r < 16; ++r) { const int rel = rel0 + crow(r, hi); if (rel > 128 || rel < -128) p0[r] = -1e30f; if (rel + 32 > 128 || rel + 32 < -128) p1[r] = -1e30f; }
;         }
;     }
;     float pmax = p0[0];
; #pragma unroll
;     for (int r = 1; r < 16; ++r) pmax = fmaxf(pmax, p0[r]);
; #pragma unroll
;     for (int r = 0; r < 16; ++r) pmax = fmaxf(pmax, p1[r]);
;     { auto rr = __builtin_amdgcn_permlane32_swap(__float_as_uint(pmax), __float_as_uint(pmax), false, false);
;       pmax = fmaxf(__uint_as_float(rr[0]), __uint_as_float(rr[1])); }
;     if (__builtin_expect(__all(pmax - m_reg <= THR / SCALE), 1)) { mn = m_reg; alpha = 1.f; }
;     else { mn = fmaxf(m_reg, pmax); alpha = __builtin_amdgcn_exp2f((m_reg - mn) * C); m_reg = mn; }
;     const float mnC = -mn * C;
; #pragma unroll
;     for (int r = 0; r < 16; ++r) p0[r] = fmaf(p0[r], C, mnC);
; #pragma unroll
;     for (int r = 0; r < 16; ++r) p1[r] = fmaf(p1[r], C, mnC);
; #pragma unroll
;     for (int r = 0; r < 16; ++r) p0[r] = __builtin_amdgcn_exp2f(p0[r]);
; template <int MODE>
; __device__ __forceinline__ void qkt(f32x16& p0, f32x16& p1, const int (&ka)[4], const int (&kra)[4], const bf16x8* qr) {
;     ...
;         KRD(kb0[0], ka[0], 0); KRD(kb1[0], ka[0], 8192); KRD(kb0[1], ka[1], 0); KRD(kb1[1], ka[1], 8192);
;         KRD(kb0[2], ka[2], 0); KRD(kb1[2], ka[2], 8192); asm volatile("s_waitcnt lgkmcnt(4)" ::: "memory"); SBAR(); p0 = __builtin_amdgcn_mfma_f32_32x32x16_bf16(kb0[0], qr[0], zz, 0, 0, 0); p1 = __builtin_amdgcn_mfma_f32_32x32x16_bf16(kb1[0], qr[0], zz, 0, 0, 0);
;         KRD(kb0[0], ka[3], 0); KRD(kb1[0], ka[3], 8192); asm volatile("s_waitcnt lgkmcnt(4)" ::: "memory"); SBAR(); p0 = __builtin_amdgcn_mfma_f32_32x32x16_bf16(kb0[1], qr[1], p0, 0, 0, 0); p1 = __builtin_amdgcn_mfma_f32_32x32x16_bf16(kb1[1], qr[1], p1, 0, 0, 0);
.LBB0_252:
	v_and_b32_e32 v171, 63, v68
	v_lshlrev_b32_e32 v17, 4, v171
	v_lshlrev_b32_e32 v16, 3, v171
	v_and_b32_e32 v17, 0xc0, v17
	v_lshlrev_b32_e32 v18, 1, v171
	v_and_or_b32 v17, v16, 24, v17
	v_and_b32_e32 v18, 32, v18
	v_and_b32_e32 v16, 0x100, v16
	v_or3_b32 v16, v17, v18, v16
	v_lshlrev_b32_e32 v172, 4, v166
	v_lshlrev_b32_e32 v17, 4, v68
	v_add_u32_e32 v173, 0, v16
	v_lshl_add_u32 v16, v165, 8, s2
	v_and_b32_e32 v17, 0x70, v17
	v_or_b32_e32 v18, 32, v172
	v_xad_u32 v175, v18, v17, v16
	v_or_b32_e32 v18, 64, v172
	v_xad_u32 v176, v18, v17, v16
	v_or_b32_e32 v18, 0x60, v172
	v_xad_u32 v174, v172, v17, v16
	v_xad_u32 v177, v18, v17, v16
	ds_read_b128 v[16:19], v174 offset:0
	ds_read_b128 v[20:23], v174 offset:0x2000
	ds_read_b128 v[72:75], v175 offset:0
	ds_read_b128 v[76:79], v175 offset:0x2000
	ds_read_b128 v[80:83], v176 offset:0
	s_and_b32 s0, s26, 0x3fffffc0
	ds_read_b128 v[84:87], v176 offset:0x2000
	s_lshl_b32 s0, s0, 2
	s_waitcnt lgkmcnt(4)
	s_add_i32 s26, s0, 0
	s_add_i32 s26, s26, 0x22000
	v_mov_b32_e32 v1, v0
	v_mov_b32_e32 v2, v0
	v_mov_b32_e32 v3, v0
	v_mov_b32_e32 v4, v0
	v_mov_b32_e32 v5, v0
	v_mov_b32_e32 v6, v0
	v_mov_b32_e32 v7, v0
	v_mov_b32_e32 v8, v0
	v_mov_b32_e32 v9, v0
	v_mov_b32_e32 v10, v0
	v_mov_b32_e32 v11, v0
	v_mov_b32_e32 v12, v0
	v_mov_b32_e32 v13, v0
	v_mov_b32_e32 v14, v0
	v_mov_b32_e32 v15, v0
	s_mov_b32 s0, 3
	s_mov_b32 s27, 4
	s_mov_b32 s28, 1
	v_mfma_f32_32x32x16_bf16 v[32:47], v[16:19], v[96:99], 0
	ds_read_b128 v[88:91], v177 offset:0
	ds_read_b128 v[92:95], v177 offset:0x2000
	s_waitcnt lgkmcnt(4)
	v_mfma_f32_32x32x16_bf16 v[16:31], v[20:23], v[96:99], 0
	v_mfma_f32_32x32x16_bf16 v[32:47], v[72:75], v[112:115], v[32:47]
	ds_read_b128 v[72:75], v174 offset:0x80
	v_mfma_f32_32x32x16_bf16 v[16:31], v[76:79], v[112:115], v[16:31]
	ds_read_b128 v[76:79], v174 offset:0x2080
	s_waitcnt lgkmcnt(4)
	v_mfma_f32_32x32x16_bf16 v[32:47], v[80:83], v[100:103], v[32:47]
	ds_read_b128 v[80:83], v175 offset:0x80
	v_mfma_f32_32x32x16_bf16 v[16:31], v[84:87], v[100:103], v[16:31]
	ds_read_b128 v[84:87], v175 offset:0x2080
	s_waitcnt lgkmcnt(4)
	v_mfma_f32_32x32x16_bf16 v[32:47], v[88:91], v[116:119], v[32:47]
	ds_read_b128 v[88:91], v176 offset:0x80
	v_mfma_f32_32x32x16_bf16 v[16:31], v[92:95], v[116:119], v[16:31]
	ds_read_b128 v[92:95], v176 offset:0x2080
	s_waitcnt lgkmcnt(4)
	v_mfma_f32_32x32x16_bf16 v[32:47], v[72:75], v[104:107], v[32:47]
	ds_read_b128 v[72:75], v177 offset:0x80
	v_mfma_f32_32x32x16_bf16 v[16:31], v[76:79], v[104:107], v[16:31]
	ds_read_b128 v[76:79], v177 offset:0x2080
	s_waitcnt lgkmcnt(4)
	v_mfma_f32_32x32x16_bf16 v[32:47], v[80:83], v[120:123], v[32:47]
	s_waitcnt lgkmcnt(2)
	v_mfma_f32_32x32x16_bf16 v[16:31], v[84:87], v[120:123], v[16:31]
	v_mfma_f32_32x32x16_bf16 v[32:47], v[88:91], v[108:111], v[32:47]
	s_waitcnt lgkmcnt(0)
	v_mfma_f32_32x32x16_bf16 v[16:31], v[92:95], v[108:111], v[16:31]
	v_mfma_f32_32x32x16_bf16 v[32:47], v[72:75], v[124:127], v[32:47]
	s_barrier
	v_cmp_gt_u32_e64 s[6:7], 32, v171
	v_lshl_add_u32 v179, v165, 2, s26
	s_mov_b32 s33, 0
	s_mov_b32 s31, 0
	s_nop 6
	v_max_f32_e32 v68, v33, v33
	v_max_f32_e32 v71, v32, v32
	v_mfma_f32_32x32x16_bf16 v[16:31], v[76:79], v[124:127], v[16:31]
	v_max_f32_e32 v68, v71, v68
	v_max3_f32 v68, v68, v34, v35
	v_max3_f32 v68, v68, v36, v37
	v_max3_f32 v68, v68, v38, v39
	v_max3_f32 v68, v68, v40, v41
	v_max3_f32 v68, v68, v42, v43
	v_max3_f32 v68, v68, v44, v45
	v_max3_f32 v68, v68, v46, v47
	s_nop 3
	v_max3_f32 v68, v68, v16, v17
	v_max3_f32 v68, v68, v18, v19
	v_max3_f32 v68, v68, v20, v21
	v_max3_f32 v68, v68, v22, v23
	v_max3_f32 v68, v68, v24, v25
	v_max3_f32 v68, v68, v26, v27
	v_max3_f32 v68, v68, v28, v29
	v_max3_f32 v68, v68, v30, v31
	v_mov_b32_e32 v71, v68
	s_nop 1
	v_permlane32_swap_b32_e32 v68, v71
	v_max_f32_e32 v71, v71, v71
	v_max_f32_e32 v68, v68, v68
	v_max_f32_e32 v68, v68, v71
	v_add_f32_e32 v71, 0x46ea6000, v68
	v_cmp_ge_f32_e32 vcc, s91, v71
	s_cmp_eq_u64 vcc, exec
	s_cselect_b64 vcc, -1, 0
	v_max_f32_e32 v68, 0xc6ea6000, v68
	v_cndmask_b32_e32 v178, v68, v193, vcc
	v_mul_f32_e32 v71, 0xbe0293ee, v178
	v_fmamk_f32 v32, v32, 0x3e0293ee, v71
	v_fmamk_f32 v33, v33, 0x3e0293ee, v71
	v_fmamk_f32 v34, v34, 0x3e0293ee, v71
	v_fmamk_f32 v35, v35, 0x3e0293ee, v71
	v_fmamk_f32 v36, v36, 0x3e0293ee, v71
	v_fmamk_f32 v37, v37, 0x3e0293ee, v71
	v_fmamk_f32 v38, v38, 0x3e0293ee, v71
	v_fmamk_f32 v39, v39, 0x3e0293ee, v71
	v_fmamk_f32 v40, v40, 0x3e0293ee, v71
	v_fmamk_f32 v41, v41, 0x3e0293ee, v71
	v_fmamk_f32 v42, v42, 0x3e0293ee, v71
	v_fmamk_f32 v43, v43, 0x3e0293ee, v71
	v_fmamk_f32 v44, v44, 0x3e0293ee, v71
	v_fmamk_f32 v45, v45, 0x3e0293ee, v71
	v_fmamk_f32 v46, v46, 0x3e0293ee, v71
	v_fmamk_f32 v47, v47, 0x3e0293ee, v71
	v_fmamk_f32 v16, v16, 0x3e0293ee, v71
	v_fmamk_f32 v17, v17, 0x3e0293ee, v71
	v_fmamk_f32 v18, v18, 0x3e0293ee, v71
	v_fmamk_f32 v19, v19, 0x3e0293ee, v71
	v_fmamk_f32 v20, v20, 0x3e0293ee, v71
	v_fmamk_f32 v21, v21, 0x3e0293ee, v71
	v_fmamk_f32 v22, v22, 0x3e0293ee, v71
	v_fmamk_f32 v23, v23, 0x3e0293ee, v71
	v_fmamk_f32 v24, v24, 0x3e0293ee, v71
	v_fmamk_f32 v25, v25, 0x3e0293ee, v71
	v_fmamk_f32 v26, v26, 0x3e0293ee, v71
	v_fmamk_f32 v27, v27, 0x3e0293ee, v71
	v_fmamk_f32 v28, v28, 0x3e0293ee, v71
	v_fmamk_f32 v29, v29, 0x3e0293ee, v71
	v_fmamk_f32 v30, v30, 0x3e0293ee, v71
	v_fmac_f32_e32 v71, 0x3e0293ee, v31
	v_exp_f32_e32 v31, v32
	v_exp_f32_e32 v32, v33
	v_exp_f32_e32 v33, v34
	v_exp_f32_e32 v34, v35
	v_exp_f32_e32 v35, v36
	v_exp_f32_e32 v36, v37
	v_exp_f32_e32 v37, v38
	v_exp_f32_e32 v38, v39
	v_exp_f32_e32 v39, v40
	v_exp_f32_e32 v40, v41
	v_exp_f32_e32 v41, v42
	v_exp_f32_e32 v42, v43
; #define SLOAD(k0) SLOADX(sg, k0)
; __device__ __forceinline__ void finishSM(f32x16& p0, f32x16& p1, float alpha, float& l_reg, bf16x8& pa0, bf16x8& pa1, bf16x8& pa2, bf16x8& pa3) {
; #pragma unroll
;     for (int r = 0; r < 16; ++r) p1[r] = __builtin_amdgcn_exp2f(p1[r]);
;     float ps = 0;
; #pragma unroll
;     for (int r = 0; r < 16; ++r) ps += p0[r];
; #pragma unroll
;     for (int r = 0; r < 16; ++r) ps += p1[r];
;     { auto rr = __builtin_amdgcn_permlane32_swap(__float_as_uint(ps), __float_as_uint(ps), false, false);
;       ps = __uint_as_float(rr[0]) + __uint_as_float(rr[1]); }
;     l_reg = l_reg * alpha + ps;
;     ...
;     PK4(p0, 0, pa0); PK4(p0, 8, pa1); PK4(p1, 0, pa2); PK4(p1, 8, pa3);
; template <int MODE> ...
;     ...
;     if (2 < NT) { asm volatile("s_waitcnt vmcnt(0)" ::: "memory"); SWRITEX(sg, 2, 2); } if (3 < NT) SLOAD(3 * 64);
;     __syncthreads();
	v_exp_f32_e32 v43, v44
	v_exp_f32_e32 v44, v45
	v_exp_f32_e32 v45, v46
	v_exp_f32_e32 v46, v47
	v_exp_f32_e32 v47, v71
	v_add_f32_e32 v71, 0, v31
	v_add_f32_e32 v71, v32, v71
	v_add_f32_e32 v71, v33, v71
	v_add_f32_e32 v71, v34, v71
	v_add_f32_e32 v71, v35, v71
	v_add_f32_e32 v71, v36, v71
	v_add_f32_e32 v71, v37, v71
	v_add_f32_e32 v71, v38, v71
	v_add_f32_e32 v71, v39, v71
	v_add_f32_e32 v71, v40, v71
	v_add_f32_e32 v71, v41, v71
	v_add_f32_e32 v71, v42, v71
	v_exp_f32_e32 v16, v16
	v_add_f32_e32 v71, v43, v71
	v_add_f32_e32 v71, v44, v71
	v_add_f32_e32 v71, v45, v71
	v_exp_f32_e32 v17, v17
	v_add_f32_e32 v71, v46, v71
	s_add_i32 s2, 0, 0x18000
	v_add_f32_e32 v71, v16, v71
	v_cvt_pk_bf16_f32 v144, v31, v32
	v_cvt_pk_bf16_f32 v145, v33, v34
	v_cvt_pk_bf16_f32 v146, v35, v36
	v_cvt_pk_bf16_f32 v147, v37, v38
	v_cvt_pk_bf16_f32 v148, v39, v40
	v_cvt_pk_bf16_f32 v149, v41, v42
	v_cvt_pk_bf16_f32 v150, v43, v44
	v_cvt_pk_bf16_f32 v151, v45, v46
	v_cvt_pk_bf16_f32 v152, v16, v17
	v_add_u32_e32 v16, s2, v169
	v_exp_f32_e32 v18, v18
	v_exp_f32_e32 v19, v19
	v_exp_f32_e32 v20, v20
	v_exp_f32_e32 v21, v21
	v_exp_f32_e32 v22, v22
	v_exp_f32_e32 v23, v23
	v_exp_f32_e32 v24, v24
	v_exp_f32_e32 v25, v25
	v_exp_f32_e32 v26, v26
	v_exp_f32_e32 v27, v27
	v_exp_f32_e32 v28, v28
	v_exp_f32_e32 v29, v29
	v_exp_f32_e32 v30, v30
	v_cvt_pk_bf16_f32 v153, v18, v19
	v_cvt_pk_bf16_f32 v154, v20, v21
	v_cvt_pk_bf16_f32 v155, v22, v23
	v_cvt_pk_bf16_f32 v156, v24, v25
	v_cvt_pk_bf16_f32 v157, v26, v27
	v_cvt_pk_bf16_f32 v158, v28, v29
	v_cvt_pk_bf16_f32 v159, v30, v47
	s_waitcnt vmcnt(0)
	s_waitcnt vmcnt(3)
	ds_write_b128 v69, v[48:51] offset:32768
	s_waitcnt vmcnt(2)
	ds_write_b128 v70, v[56:59] offset:32768
	s_waitcnt vmcnt(1)
	ds_write_b128 v16, v[52:55]
	v_add_u32_e32 v16, s2, v170
	s_add_u32 s2, s8, 0x1e0000
	s_addc_u32 s3, s9, 0
	v_add_f32_e32 v71, v17, v71
	s_waitcnt vmcnt(0)
	ds_write_b128 v16, v[60:63]
	v_lshl_add_u64 v[16:17], s[2:3], 0, v[66:67]
	global_load_dwordx4 v[128:131], v[16:17], off
	v_lshl_add_u64 v[16:17], s[2:3], 0, v[64:65]
	s_add_u32 s2, s8, 0x1e0400
	s_addc_u32 s3, s9, 0
	global_load_dwordx4 v[132:135], v[16:17], off
	v_lshl_add_u64 v[16:17], s[2:3], 0, v[66:67]
	global_load_dwordx4 v[136:139], v[16:17], off
	v_lshl_add_u64 v[16:17], s[2:3], 0, v[64:65]
	global_load_dwordx4 v[140:143], v[16:17], off
	v_add_f32_e32 v71, v18, v71
	v_add_f32_e32 v71, v19, v71
	v_add_f32_e32 v71, v20, v71
	v_add_f32_e32 v71, v21, v71
	v_add_f32_e32 v71, v22, v71
	v_add_f32_e32 v71, v23, v71
	v_add_f32_e32 v71, v24, v71
	v_add_f32_e32 v71, v25, v71
	v_add_f32_e32 v71, v26, v71
	v_add_f32_e32 v71, v27, v71
	v_sub_f32_e32 v17, 0xc6ea6000, v68
	v_add_f32_e32 v71, v28, v71
	v_mul_f32_e32 v17, 0x3e0293ee, v17
	v_add_f32_e32 v71, v29, v71
	v_exp_f32_e32 v17, v17
	s_mul_i32 s2, s24, 0xa0000
	v_add_f32_e32 v71, v30, v71
	s_add_i32 s2, s2, 0xffc00000
	s_lshr_b32 s94, s4, 2
	v_add_f32_e32 v71, v47, v71
	s_add_u32 s30, s2, 0x360000
	s_mul_hi_u32 s8, s5, 0x2800
	s_mulk_i32 s5, 0x2800
	s_lshl_b64 s[2:3], s[94:95], 8
	v_mov_b32_e32 v72, v71
	s_add_u32 s2, s5, s2
	s_nop 0
	v_permlane32_swap_b32_e32 v71, v72
	v_mul_f32_e32 v17, 0, v17
	s_addc_u32 s3, s8, s3
	v_add_f32_e32 v16, v71, v72
	v_cndmask_b32_e64 v17, v17, 0, vcc
	s_add_u32 s2, s80, s2
	v_add_f32_e32 v180, v16, v17
	s_addc_u32 s3, s81, s3
	v_mov_b64_e32 v[62:63], v[14:15]
	v_mov_b64_e32 v[46:47], v[14:15]
	v_mov_b64_e32 v[30:31], v[14:15]
	v_permlane32_swap_b32_e32 v144, v146
	v_permlane32_swap_b32_e32 v145, v147
	v_permlane32_swap_b32_e32 v148, v150
	v_permlane32_swap_b32_e32 v149, v151
	v_permlane32_swap_b32_e32 v152, v154
	v_permlane32_swap_b32_e32 v153, v155
	v_permlane32_swap_b32_e32 v156, v158
	v_permlane32_swap_b32_e32 v157, v159
	v_lshl_add_u64 v[160:161], s[2:3], 0, v[66:67]
	v_lshl_add_u64 v[162:163], s[2:3], 0, v[64:65]
	s_mov_b64 s[2:3], 0
	v_mov_b64_e32 v[60:61], v[12:13]
	v_mov_b64_e32 v[58:59], v[10:11]
	v_mov_b64_e32 v[56:57], v[8:9]
	v_mov_b64_e32 v[54:55], v[6:7]
	v_mov_b64_e32 v[52:53], v[4:5]
	v_mov_b64_e32 v[50:51], v[2:3]
	v_mov_b64_e32 v[48:49], v[0:1]
	v_mov_b64_e32 v[44:45], v[12:13]
	v_mov_b64_e32 v[42:43], v[10:11]
	v_mov_b64_e32 v[40:41], v[8:9]
	v_mov_b64_e32 v[38:39], v[6:7]
	v_mov_b64_e32 v[36:37], v[4:5]
	v_mov_b64_e32 v[34:35], v[2:3]
	v_mov_b64_e32 v[32:33], v[0:1]
	v_mov_b64_e32 v[28:29], v[12:13]
	v_mov_b64_e32 v[26:27], v[10:11]
	v_mov_b64_e32 v[24:25], v[8:9]
	v_mov_b64_e32 v[22:23], v[6:7]
	v_mov_b64_e32 v[20:21], v[4:5]
	v_mov_b64_e32 v[18:19], v[2:3]
	v_mov_b64_e32 v[16:17], v[0:1]
	s_waitcnt lgkmcnt(0)
	v_readfirstlane_b32 s4, v201
	s_nop 3
	s_lshr_b32 s4, s4, 6
	s_cmp_ge_u32 s4, 4
	s_cbranch_scc1 .Lprio_m2
	s_setprio 1
.Lprio_m2:
	s_barrier
; template <int MODE>
; __device__ __forceinline__ void qkt(f32x16& p0, f32x16& p1, const int (&ka)[4], const int (&kra)[4], const bf16x8* qr) {
;     ...
;         KRD(kb0[0], ka[0], 0); KRD(kb1[0], ka[0], 8192); KRD(kb0[1], ka[1], 0); KRD(kb1[1], ka[1], 8192);
;         KRD(kb0[2], ka[2], 0); KRD(kb1[2], ka[2], 8192); asm volatile("s_waitcnt lgkmcnt(4)" ::: "memory"); SBAR(); p0 = __builtin_amdgcn_mfma_f32_32x32x16_bf16(kb0[0], qr[0], zz, 0, 0, 0); p1 = __builtin_amdgcn_mfma_f32_32x32x16_bf16(kb1[0], qr[0], zz, 0, 0, 0);
;         KRD(kb0[0], ka[3], 0); KRD(kb1[0], ka[3], 8192); asm volatile("s_waitcnt lgkmcnt(4)" ::: "memory"); SBAR(); p0 = __builtin_amdgcn_mfma_f32_32x32x16_bf16(kb0[1], qr[1], p0, 0, 0, 0); p1 = __builtin_amdgcn_mfma_f32_32x32x16_bf16(kb1[1], qr[1], p1, 0, 0, 0);
;         KRD(kb0[1], ka[0], 128); KRD(kb1[1], ka[0], 8320); asm volatile("s_waitcnt lgkmcnt(4)" ::: "memory"); SBAR(); p0 = __builtin_amdgcn_mfma_f32_32x32x16_bf16(kb0[2], qr[2], p0, 0, 0, 0); p1 = __builtin_amdgcn_mfma_f32_32x32x16_bf16(kb1[2], qr[2], p1, 0, 0, 0);
;         KRD(kb0[2], ka[1], 128); KRD(kb1[2], ka[1], 8320); asm volatile("s_waitcnt lgkmcnt(4)" ::: "memory"); SBAR(); p0 = __builtin_amdgcn_mfma_f32_32x32x16_bf16(kb0[0], qr[3], p0, 0, 0, 0); p1 = __builtin_amdgcn_mfma_f32_32x32x16_bf16(kb1[0], qr[3], p1, 0, 0, 0);
;         KRD(kb0[0], ka[2], 128); KRD(kb1[0], ka[2], 8320); asm volatile("s_waitcnt lgkmcnt(4)" ::: "memory"); SBAR(); p0 = __builtin_amdgcn_mfma_f32_32x32x16_bf16(kb0[1], qr[4], p0, 0, 0, 0); p1 = __builtin_amdgcn_mfma_f32_32x32x16_bf16(kb1[1], qr[4], p1, 0, 0, 0);
;         KRD(kb0[1], ka[3], 128); KRD(kb1[1], ka[3], 8320); asm volatile("s_waitcnt lgkmcnt(4)" ::: "memory"); SBAR(); p0 = __builtin_amdgcn_mfma_f32_32x32x16_bf16(kb0[2], qr[5], p0, 0, 0, 0); p1 = __builtin_amdgcn_mfma_f32_32x32x16_bf16(kb1[2], qr[5], p1, 0, 0, 0);
;         asm volatile("s_waitcnt lgkmcnt(2)" ::: "memory"); SBAR(); p0 = __builtin_amdgcn_mfma_f32_32x32x16_bf16(kb0[0], qr[6], p0, 0, 0, 0); p1 = __builtin_amdgcn_mfma_f32_32x32x16_bf16(kb1[0], qr[6], p1, 0, 0, 0);
;         asm volatile("s_waitcnt lgkmcnt(0)" ::: "memory"); SBAR(); p0 = __builtin_amdgcn_mfma_f32_32x32x16_bf16(kb0[1], qr[7], p0, 0, 0, 0); p1 = __builtin_amdgcn_mfma_f32_32x32x16_bf16(kb1[1], qr[7], p1, 0, 0, 0);
; template <int D0> __device__ __forceinline__ void vread(VFr& f, int vb) {
.LBB0_253:
	s_lshl_b32 s4, s28, 14
	v_add_u32_e32 v188, s4, v174
	v_add_u32_e32 v191, s4, v175
	v_add_u32_e32 v238, s4, v176
	v_add_u32_e32 v239, s4, v177
	v_lshl_add_u32 v240, s31, 14, v173
	ds_read_b64_tr_b16 v[182:183], v240 offset:0
	ds_read_b64_tr_b16 v[184:185], v240 offset:0x800
	ds_read_b64_tr_b16 v[202:203], v240 offset:0x1000
	ds_read_b64_tr_b16 v[204:205], v240 offset:0x1800
	ds_read_b64_tr_b16 v[206:207], v240 offset:0x2000
	ds_read_b64_tr_b16 v[208:209], v240 offset:0x2800
	ds_read_b64_tr_b16 v[210:211], v240 offset:0x3000
	ds_read_b64_tr_b16 v[212:213], v240 offset:0x3800
	ds_read_b128 v[64:67], v188 offset:0
	ds_read_b128 v[68:71], v188 offset:0x2000
	ds_read_b128 v[214:217], v191 offset:0
	ds_read_b128 v[218:221], v191 offset:0x2000
	ds_read_b128 v[222:225], v238 offset:0
	ds_read_b128 v[226:229], v238 offset:0x2000
	s_waitcnt lgkmcnt(4)
	s_nop 0
	v_mfma_f32_32x32x16_bf16 v[80:95], v[64:67], v[96:99], 0
	ds_read_b128 v[230:233], v239 offset:0
	ds_read_b128 v[234:237], v239 offset:0x2000
	s_waitcnt lgkmcnt(4)
	v_mfma_f32_32x32x16_bf16 v[64:79], v[68:71], v[96:99], 0
	v_mfma_f32_32x32x16_bf16 v[80:95], v[214:217], v[112:115], v[80:95]
	ds_read_b128 v[214:217], v188 offset:0x80
	v_mfma_f32_32x32x16_bf16 v[64:79], v[218:221], v[112:115], v[64:79]
	ds_read_b128 v[218:221], v188 offset:0x2080
	s_waitcnt lgkmcnt(4)
	v_mfma_f32_32x32x16_bf16 v[80:95], v[222:225], v[100:103], v[80:95]
	ds_read_b128 v[222:225], v191 offset:0x80
	v_mfma_f32_32x32x16_bf16 v[64:79], v[226:229], v[100:103], v[64:79]
	ds_read_b128 v[226:229], v191 offset:0x2080
	s_waitcnt lgkmcnt(4)
	v_mfma_f32_32x32x16_bf16 v[80:95], v[230:233], v[116:119], v[80:95]
	ds_read_b128 v[230:233], v238 offset:0x80
	v_mfma_f32_32x32x16_bf16 v[64:79], v[234:237], v[116:119], v[64:79]
	ds_read_b128 v[234:237], v238 offset:0x2080
	s_waitcnt lgkmcnt(4)
	v_mfma_f32_32x32x16_bf16 v[80:95], v[214:217], v[104:107], v[80:95]
	ds_read_b128 v[214:217], v239 offset:0x80
	v_mfma_f32_32x32x16_bf16 v[64:79], v[218:221], v[104:107], v[64:79]
	ds_read_b128 v[218:221], v239 offset:0x2080
	s_waitcnt lgkmcnt(4)
	v_mfma_f32_32x32x16_bf16 v[80:95], v[222:225], v[120:123], v[80:95]
	s_waitcnt lgkmcnt(2)
	v_mfma_f32_32x32x16_bf16 v[64:79], v[226:229], v[120:123], v[64:79]
	v_mfma_f32_32x32x16_bf16 v[80:95], v[230:233], v[108:111], v[80:95]
	s_waitcnt lgkmcnt(0)
	v_mfma_f32_32x32x16_bf16 v[64:79], v[234:237], v[108:111], v[64:79]
	v_mfma_f32_32x32x16_bf16 v[80:95], v[214:217], v[124:127], v[80:95]
	ds_read_b64_tr_b16 v[214:215], v240 offset:0x200
	ds_read_b64_tr_b16 v[216:217], v240 offset:0xa00
	v_mfma_f32_32x32x16_bf16 v[64:79], v[218:221], v[124:127], v[64:79]
	ds_read_b64_tr_b16 v[218:219], v240 offset:0x1200
	ds_read_b64_tr_b16 v[220:221], v240 offset:0x1a00
	ds_read_b64_tr_b16 v[222:223], v240 offset:0x2200
	ds_read_b64_tr_b16 v[224:225], v240 offset:0x2a00
	ds_read_b64_tr_b16 v[226:227], v240 offset:0x3200
	ds_read_b64_tr_b16 v[228:229], v240 offset:0x3a00
	s_waitcnt lgkmcnt(8)
	v_mfma_f32_32x32x16_bf16 v[0:15], v[144:147], v[182:185], v[0:15]
	ds_read_b64_tr_b16 v[182:183], v240 offset:0x400
	ds_read_b64_tr_b16 v[184:185], v240 offset:0xc00
	v_mfma_f32_32x32x16_bf16 v[0:15], v[148:151], v[202:205], v[0:15]
	ds_read_b64_tr_b16 v[202:203], v240 offset:0x1400
	ds_read_b64_tr_b16 v[204:205], v240 offset:0x1c00
	v_mfma_f32_32x32x16_bf16 v[0:15], v[152:155], v[206:209], v[0:15]
	ds_read_b64_tr_b16 v[206:207], v240 offset:0x2400
	ds_read_b64_tr_b16 v[208:209], v240 offset:0x2c00
	v_mfma_f32_32x32x16_bf16 v[0:15], v[156:159], v[210:213], v[0:15]
	ds_read_b64_tr_b16 v[210:211], v240 offset:0x3400
	ds_read_b64_tr_b16 v[212:213], v240 offset:0x3c00
	s_waitcnt lgkmcnt(8)
	v_mfma_f32_32x32x16_bf16 v[48:63], v[144:147], v[214:217], v[48:63]
	ds_read_b64_tr_b16 v[214:215], v240 offset:0x600
	ds_read_b64_tr_b16 v[216:217], v240 offset:0xe00
	v_mfma_f32_32x32x16_bf16 v[48:63], v[148:151], v[218:221], v[48:63]
	ds_read_b64_tr_b16 v[218:219], v240 offset:0x1600
	ds_read_b64_tr_b16 v[220:221], v240 offset:0x1e00
	v_mfma_f32_32x32x16_bf16 v[48:63], v[152:155], v[222:225], v[48:63]
	ds_read_b64_tr_b16 v[222:223], v240 offset:0x2600
	ds_read_b64_tr_b16 v[224:225], v240 offset:0x2e00
	v_mfma_f32_32x32x16_bf16 v[48:63], v[156:159], v[226:229], v[48:63]
	ds_read_b64_tr_b16 v[226:227], v240 offset:0x3600
	ds_read_b64_tr_b16 v[228:229], v240 offset:0x3e00
	s_waitcnt lgkmcnt(8)
	v_mfma_f32_32x32x16_bf16 v[32:47], v[144:147], v[182:185], v[32:47]
	s_waitcnt lgkmcnt(0)
	v_mfma_f32_32x32x16_bf16 v[32:47], v[148:151], v[202:205], v[32:47]
	v_mfma_f32_32x32x16_bf16 v[32:47], v[152:155], v[206:209], v[32:47]
	v_mfma_f32_32x32x16_bf16 v[32:47], v[156:159], v[210:213], v[32:47]
	v_mfma_f32_32x32x16_bf16 v[16:31], v[144:147], v[214:217], v[16:31]
	v_max_f32_e32 v144, v81, v81
	v_max_f32_e32 v145, v80, v80
	v_max_f32_e32 v144, v145, v144
	v_max3_f32 v144, v144, v82, v83
	v_max3_f32 v144, v144, v84, v85
	v_max3_f32 v144, v144, v86, v87
	v_max3_f32 v144, v144, v88, v89
	v_max3_f32 v144, v144, v90, v91
	v_max3_f32 v144, v144, v92, v93
	v_mfma_f32_32x32x16_bf16 v[16:31], v[148:151], v[218:221], v[16:31]
	v_max3_f32 v144, v144, v94, v95
	v_max3_f32 v144, v144, v64, v65
	v_max3_f32 v144, v144, v66, v67
	v_max3_f32 v144, v144, v68, v69
	v_max3_f32 v144, v144, v70, v71
	v_max3_f32 v144, v144, v72, v73
	v_max3_f32 v144, v144, v74, v75
	v_max3_f32 v144, v144, v76, v77
	v_mfma_f32_32x32x16_bf16 v[16:31], v[152:155], v[222:225], v[16:31]
	v_max3_f32 v144, v144, v78, v79
	v_mov_b32_e32 v145, v144
	s_nop 1
	v_permlane32_swap_b32_e32 v144, v145
	v_max_f32_e32 v145, v145, v145
	v_max_f32_e32 v144, v144, v144
	v_max_f32_e32 v144, v144, v145
	v_sub_f32_e32 v145, v144, v178
	v_cmp_ge_f32_e32 vcc, s91, v145
	v_max_f32_e32 v145, v178, v178
	v_max_f32_e32 v144, v145, v144
	v_mfma_f32_32x32x16_bf16 v[16:31], v[156:159], v[226:229], v[16:31]
	v_sub_f32_e32 v145, v178, v144
	v_mul_f32_e32 v145, 0x3e0293ee, v145
	v_exp_f32_e32 v145, v145
	s_cmp_eq_u64 vcc, exec
	s_cselect_b64 s[8:9], -1, 0
	v_cndmask_b32_e64 v182, v145, 1.0, s[8:9]
	v_cmp_gt_f32_e32 vcc, 1.0, v182
	s_barrier
; #define RESC(a) do { if (__any((a) < 1.f)) { if (hi == 0) al_l[r32] = (a); asm volatile("s_waitcnt lgkmcnt(0)" ::: "memory"); \
;     _Pragma("unroll") for (int d = 0; d < 4; ++d) _Pragma("unroll") for (int r = 0; r < 16; ++r) o[d][r] *= al_l[crow(r, hi)]; } } while (0)
; template <int MODE> ...
;     ...
;         if (ACT(j)) { partialSM<MODE>(p0, p1, m_reg, mn, al, REL0(j), hi, NEEDM(j)); RESC(al); finishSM(p0, p1, al, l_reg, pa0, pa1, pa2, pa3); }
	s_cbranch_vccz .LBB0_257
	s_and_saveexec_b64 s[4:5], s[6:7]
	ds_write_b32 v179, v182 offset:128
	s_or_b64 exec, exec, s[4:5]
	s_waitcnt lgkmcnt(0)
	v_add_u32_e32 v145, s26, v172
	ds_read_b128 v[146:149], v145 offset:224
	ds_read_b128 v[150:153], v145 offset:192
	ds_read_b128 v[154:157], v145 offset:160
	ds_read_b128 v[202:205], v145 offset:128
	s_waitcnt lgkmcnt(3)
	v_pk_mul_f32 v[12:13], v[12:13], v[146:147]
	s_waitcnt lgkmcnt(2)
	v_pk_mul_f32 v[8:9], v[8:9], v[150:151]
	s_waitcnt lgkmcnt(1)
	v_pk_mul_f32 v[4:5], v[4:5], v[154:155]
	v_pk_mul_f32 v[14:15], v[14:15], v[148:149]
	v_pk_mul_f32 v[10:11], v[10:11], v[152:153]
	v_pk_mul_f32 v[6:7], v[6:7], v[156:157]
	s_waitcnt lgkmcnt(0)
	v_pk_mul_f32 v[2:3], v[2:3], v[204:205]
	v_pk_mul_f32 v[0:1], v[0:1], v[202:203]
	v_pk_mul_f32 v[60:61], v[60:61], v[146:147]
	v_pk_mul_f32 v[56:57], v[56:57], v[150:151]
	v_pk_mul_f32 v[52:53], v[52:53], v[154:155]
	v_pk_mul_f32 v[62:63], v[62:63], v[148:149]
	v_pk_mul_f32 v[58:59], v[58:59], v[152:153]
	v_pk_mul_f32 v[54:55], v[54:55], v[156:157]
	v_pk_mul_f32 v[50:51], v[50:51], v[204:205]
	v_pk_mul_f32 v[48:49], v[48:49], v[202:203]
	v_pk_mul_f32 v[44:45], v[44:45], v[146:147]
	v_pk_mul_f32 v[40:41], v[40:41], v[150:151]
	v_pk_mul_f32 v[36:37], v[36:37], v[154:155]
	v_pk_mul_f32 v[46:47], v[46:47], v[148:149]
	v_pk_mul_f32 v[42:43], v[42:43], v[152:153]
	v_pk_mul_f32 v[38:39], v[38:39], v[156:157]
	v_pk_mul_f32 v[34:35], v[34:35], v[204:205]
	v_pk_mul_f32 v[32:33], v[32:33], v[202:203]
	v_pk_mul_f32 v[28:29], v[28:29], v[146:147]
	v_pk_mul_f32 v[24:25], v[24:25], v[150:151]
	v_pk_mul_f32 v[20:21], v[20:21], v[154:155]
	v_pk_mul_f32 v[30:31], v[30:31], v[148:149]
	v_pk_mul_f32 v[26:27], v[26:27], v[152:153]
	v_pk_mul_f32 v[22:23], v[22:23], v[156:157]
	v_pk_mul_f32 v[18:19], v[18:19], v[204:205]
	v_pk_mul_f32 v[16:17], v[16:17], v[202:203]

; #define SBAR() __builtin_amdgcn_sched_barrier(0)
; template <int D0> __device__ __forceinline__ void vread(VFr& f, int vb) {
;     f.l0 = tr_read<v_rd_off(D0, 0, 0)>(vb); f.h0 = tr_read<v_rd_off(D0, 0, 1)>(vb); f.l1 = tr_read<v_rd_off(D0, 1, 0)>(vb); f.h1 = tr_read<v_rd_off(D0, 1, 1)>(vb);
;     f.l2 = tr_read<v_rd_off(D0, 2, 0)>(vb); f.h2 = tr_read<v_rd_off(D0, 2, 1)>(vb); f.l3 = tr_read<v_rd_off(D0, 3, 0)>(vb); f.h3 = tr_read<v_rd_off(D0, 3, 1)>(vb);
; }
; __device__ __forceinline__ void vmma(f32x16& od, const VFr& f, bf16x8 pa0, bf16x8 pa1, bf16x8 pa2, bf16x8 pa3) {
;     ...
;     od = __builtin_amdgcn_mfma_f32_32x32x16_bf16(pa0, PK(f.l0, f.h0), od, 0, 0, 0);
;     od = __builtin_amdgcn_mfma_f32_32x32x16_bf16(pa1, PK(f.l1, f.h1), od, 0, 0, 0);
;     od = __builtin_amdgcn_mfma_f32_32x32x16_bf16(pa2, PK(f.l2, f.h2), od, 0, 0, 0);
;     od = __builtin_amdgcn_mfma_f32_32x32x16_bf16(pa3, PK(f.l3, f.h3), od, 0, 0, 0);
;     ...
; }
; __device__ __forceinline__ void pv_pipe(f32x16* o, int vb, VFr& fa, bf16x8 pa0, bf16x8 pa1, bf16x8 pa2, bf16x8 pa3) {
;     VFr fb;
;     vread<1>(fb, vb); asm volatile("s_waitcnt lgkmcnt(8)" ::: "memory"); SBAR(); vmma(o[0], fa, pa0, pa1, pa2, pa3);
;     vread<2>(fa, vb); asm volatile("s_waitcnt lgkmcnt(8)" ::: "memory"); SBAR(); vmma(o[1], fb, pa0, pa1, pa2, pa3);
;     vread<3>(fb, vb); asm volatile("s_waitcnt lgkmcnt(8)" ::: "memory"); SBAR(); vmma(o[2], fa, pa0, pa1, pa2, pa3);
;     asm volatile("s_waitcnt lgkmcnt(0)" ::: "memory"); SBAR(); vmma(o[3], fb, pa0, pa1, pa2, pa3);
; }
; template <int MODE> ...
;     ...
;     if constexpr (MODE != 0) { if (ACT(NT - 1)) { VFr fa; vread<0>(fa, vb0 + vp * SHM_V); pv_pipe(o, vb0 + vp * SHM_V, fa, pa0, pa1, pa2, pa3); } } else pv_d0(o, vb0 + vp * SHM_V, pa0, pa1, pa2, pa3);
.LBB0_263:
	s_setprio 0
	v_lshl_add_u32 v65, s31, 14, v173
	ds_read_b64_tr_b16 v[66:67], v65 offset:0
	ds_read_b64_tr_b16 v[68:69], v65 offset:0x800
	ds_read_b64_tr_b16 v[70:71], v65 offset:0x1000
	ds_read_b64_tr_b16 v[72:73], v65 offset:0x1800
	ds_read_b64_tr_b16 v[74:75], v65 offset:0x2000
	ds_read_b64_tr_b16 v[76:77], v65 offset:0x2800
	ds_read_b64_tr_b16 v[78:79], v65 offset:0x3000
	ds_read_b64_tr_b16 v[80:81], v65 offset:0x3800
	ds_read_b64_tr_b16 v[82:83], v65 offset:0x200
	ds_read_b64_tr_b16 v[84:85], v65 offset:0xa00
	ds_read_b64_tr_b16 v[86:87], v65 offset:0x1200
	ds_read_b64_tr_b16 v[88:89], v65 offset:0x1a00
	ds_read_b64_tr_b16 v[90:91], v65 offset:0x2200
	ds_read_b64_tr_b16 v[92:93], v65 offset:0x2a00
	ds_read_b64_tr_b16 v[94:95], v65 offset:0x3200
	ds_read_b64_tr_b16 v[96:97], v65 offset:0x3a00
	s_waitcnt lgkmcnt(8)
	s_nop 0
	v_mfma_f32_32x32x16_bf16 v[0:15], v[144:147], v[66:69], v[0:15]
	ds_read_b64_tr_b16 v[66:67], v65 offset:0x400
	ds_read_b64_tr_b16 v[68:69], v65 offset:0xc00
	v_mfma_f32_32x32x16_bf16 v[0:15], v[148:151], v[70:73], v[0:15]
	ds_read_b64_tr_b16 v[70:71], v65 offset:0x1400
	ds_read_b64_tr_b16 v[72:73], v65 offset:0x1c00
	v_mfma_f32_32x32x16_bf16 v[0:15], v[152:155], v[74:77], v[0:15]
	ds_read_b64_tr_b16 v[74:75], v65 offset:0x2400
	ds_read_b64_tr_b16 v[76:77], v65 offset:0x2c00
	v_mfma_f32_32x32x16_bf16 v[0:15], v[156:159], v[78:81], v[0:15]
	ds_read_b64_tr_b16 v[78:79], v65 offset:0x3400
	ds_read_b64_tr_b16 v[80:81], v65 offset:0x3c00
	s_waitcnt lgkmcnt(8)
	v_mfma_f32_32x32x16_bf16 v[48:63], v[144:147], v[82:85], v[48:63]
	ds_read_b64_tr_b16 v[82:83], v65 offset:0x600
	ds_read_b64_tr_b16 v[84:85], v65 offset:0xe00
	v_mfma_f32_32x32x16_bf16 v[48:63], v[148:151], v[86:89], v[48:63]
	ds_read_b64_tr_b16 v[86:87], v65 offset:0x1600
	ds_read_b64_tr_b16 v[88:89], v65 offset:0x1e00
	v_mfma_f32_32x32x16_bf16 v[48:63], v[152:155], v[90:93], v[48:63]
	ds_read_b64_tr_b16 v[90:91], v65 offset:0x2600
	ds_read_b64_tr_b16 v[92:93], v65 offset:0x2e00
	v_mfma_f32_32x32x16_bf16 v[48:63], v[156:159], v[94:97], v[48:63]
	ds_read_b64_tr_b16 v[94:95], v65 offset:0x3600
	ds_read_b64_tr_b16 v[96:97], v65 offset:0x3e00
	s_waitcnt lgkmcnt(8)
	v_mfma_f32_32x32x16_bf16 v[32:47], v[144:147], v[66:69], v[32:47]
	s_waitcnt lgkmcnt(0)
	v_mfma_f32_32x32x16_bf16 v[32:47], v[148:151], v[70:73], v[32:47]
	v_mfma_f32_32x32x16_bf16 v[32:47], v[152:155], v[74:77], v[32:47]
	v_mfma_f32_32x32x16_bf16 v[32:47], v[156:159], v[78:81], v[32:47]
	v_mfma_f32_32x32x16_bf16 v[16:31], v[144:147], v[82:85], v[16:31]
	s_cmp_eq_u32 s29, 0
	v_mfma_f32_32x32x16_bf16 v[16:31], v[148:151], v[86:89], v[16:31]
	v_mfma_f32_32x32x16_bf16 v[16:31], v[152:155], v[90:93], v[16:31]
	v_mfma_f32_32x32x16_bf16 v[16:31], v[156:159], v[94:97], v[16:31]
	s_cbranch_scc1 .LBB0_268
	s_and_saveexec_b64 s[2:3], s[6:7]

; template <int MODE>
; __device__ __forceinline__ void partialSM(f32x16& p0, f32x16& p1, float& m_reg, float& mn, float& alpha, int rel0, int hi, bool need_mask) {
;     ...
;     float pmax = p0[0];
; #pragma unroll
;     for (int r = 1; r < 16; ++r) pmax = fmaxf(pmax, p0[r]);
; #pragma unroll
;     for (int r = 0; r < 16; ++r) pmax = fmaxf(pmax, p1[r]);
;     { auto rr = __builtin_amdgcn_permlane32_swap(__float_as_uint(pmax), __float_as_uint(pmax), false, false);
;       pmax = fmaxf(__uint_as_float(rr[0]), __uint_as_float(rr[1])); }
;     if (__builtin_expect(__all(pmax - m_reg <= THR / SCALE), 1)) { mn = m_reg; alpha = 1.f; }
;     else { mn = fmaxf(m_reg, pmax); alpha = __builtin_amdgcn_exp2f((m_reg - mn) * C); m_reg = mn; }
;     const float mnC = -mn * C;
; #pragma unroll
;     for (int r = 0; r < 16; ++r) p0[r] = fmaf(p0[r], C, mnC);
; #pragma unroll
;     for (int r = 0; r < 16; ++r) p1[r] = fmaf(p1[r], C, mnC);
; #pragma unroll
;     for (int r = 0; r < 16; ++r) p0[r] = __builtin_amdgcn_exp2f(p0[r]);
; template <int MODE>
; __device__ __forceinline__ void qkt(f32x16& p0, f32x16& p1, const int (&ka)[4], const int (&kra)[4], const bf16x8* qr) {
;     ...
;     if constexpr (MODE == 0) {
;         KRD(kb0[0], ka[0], 0); KRD(kb1[0], ka[0], 8192); KRD(kb0[1], ka[1], 0); KRD(kb1[1], ka[1], 8192);
;         KRD(kb0[2], ka[2], 0); KRD(kb1[2], ka[2], 8192); asm volatile("s_waitcnt lgkmcnt(4)" ::: "memory"); SBAR(); p0 = __builtin_amdgcn_mfma_f32_32x32x16_bf16(kb0[0], qr[0], zz, 0, 0, 0); p1 = __builtin_amdgcn_mfma_f32_32x32x16_bf16(kb1[0], qr[0], zz, 0, 0, 0);
;         KRD(kb0[0], ka[3], 0); KRD(kb1[0], ka[3], 8192); asm volatile("s_waitcnt lgkmcnt(4)" ::: "memory"); SBAR(); p0 = __builtin_amdgcn_mfma_f32_32x32x16_bf16(kb0[1], qr[1], p0, 0, 0, 0); p1 = __builtin_amdgcn_mfma_f32_32x32x16_bf16(kb1[1], qr[1], p1, 0, 0, 0);
;         KRD(kb0[1], ka[0], 128); KRD(kb1[1], ka[0], 8320); asm volatile("s_waitcnt lgkmcnt(4)" ::: "memory"); SBAR(); p0 = __builtin_amdgcn_mfma_f32_32x32x16_bf16(kb0[2], qr[2], p0, 0, 0, 0); p1 = __builtin_amdgcn_mfma_f32_32x32x16_bf16(kb1[2], qr[2], p1, 0, 0, 0);
;         KRD(kb0[2], ka[1], 128); KRD(kb1[2], ka[1], 8320); asm volatile("s_waitcnt lgkmcnt(4)" ::: "memory"); SBAR(); p0 = __builtin_amdgcn_mfma_f32_32x32x16_bf16(kb0[0], qr[3], p0, 0, 0, 0); p1 = __builtin_amdgcn_mfma_f32_32x32x16_bf16(kb1[0], qr[3], p1, 0, 0, 0);
.LBB0_285:
	v_and_b32_e32 v210, 63, v76
	v_lshlrev_b32_e32 v17, 4, v210
	s_and_b32 s0, s0, 0x3fffffc0
	v_lshlrev_b32_e32 v16, 3, v210
	v_and_b32_e32 v17, 0xc0, v17
	v_lshlrev_b32_e32 v18, 1, v210
	s_lshl_b32 s0, s0, 2
	v_and_or_b32 v17, v16, 24, v17
	v_and_b32_e32 v18, 32, v18
	v_and_b32_e32 v16, 0x100, v16
	s_add_i32 s23, s0, 0
	v_or3_b32 v16, v17, v18, v16
	v_lshlrev_b32_e32 v211, 4, v204
	v_lshlrev_b32_e32 v17, 4, v76
	s_add_i32 s0, 0, 0x1c000
	v_add_u32_e32 v212, 0, v16
	v_lshl_add_u32 v16, v203, 8, s5
	v_and_b32_e32 v17, 0x70, v17
	v_lshl_add_u32 v18, v203, 7, s0
	v_and_b32_e32 v19, 0x70, v77
	v_or_b32_e32 v20, 32, v211
	v_xad_u32 v215, v20, v17, v16
	v_xad_u32 v216, v20, v19, v18
	v_or_b32_e32 v20, 64, v211
	v_xad_u32 v217, v20, v17, v16
	v_xad_u32 v218, v20, v19, v18
	v_or_b32_e32 v20, 0x60, v211
	v_xad_u32 v213, v211, v17, v16
	v_xad_u32 v214, v211, v19, v18
	v_xad_u32 v219, v20, v17, v16
	v_xad_u32 v220, v20, v19, v18
	ds_read_b128 v[16:19], v213 offset:0
	ds_read_b128 v[20:23], v213 offset:0x2000
	ds_read_b128 v[70:73], v215 offset:0
	ds_read_b128 v[80:83], v215 offset:0x2000
	ds_read_b128 v[84:87], v217 offset:0
	ds_read_b128 v[88:91], v217 offset:0x2000
	s_waitcnt lgkmcnt(4)
	s_add_i32 s23, s23, 0x22000
	v_mov_b32_e32 v1, v0
	v_mov_b32_e32 v2, v0
	v_mov_b32_e32 v3, v0
	v_mov_b32_e32 v4, v0
	v_mov_b32_e32 v5, v0
	v_mov_b32_e32 v6, v0
	v_mov_b32_e32 v7, v0
	v_mov_b32_e32 v8, v0
	v_mov_b32_e32 v9, v0
	v_mov_b32_e32 v10, v0
	v_mov_b32_e32 v11, v0
	v_mov_b32_e32 v12, v0
	v_mov_b32_e32 v13, v0
	v_mov_b32_e32 v14, v0
	v_mov_b32_e32 v15, v0
	s_mov_b32 s42, 3
	s_mov_b32 s43, 1
	v_mfma_f32_32x32x16_bf16 v[32:47], v[16:19], v[96:99], 0
	ds_read_b128 v[92:95], v219 offset:0
	ds_read_b128 v[144:147], v219 offset:0x2000
	s_waitcnt lgkmcnt(4)
	v_mfma_f32_32x32x16_bf16 v[16:31], v[20:23], v[96:99], 0
	v_mfma_f32_32x32x16_bf16 v[32:47], v[70:73], v[100:103], v[32:47]
	ds_read_b128 v[70:73], v213 offset:0x80
	v_mfma_f32_32x32x16_bf16 v[16:31], v[80:83], v[100:103], v[16:31]
	ds_read_b128 v[80:83], v213 offset:0x2080
	s_waitcnt lgkmcnt(4)
	v_mfma_f32_32x32x16_bf16 v[32:47], v[84:87], v[104:107], v[32:47]
	ds_read_b128 v[84:87], v215 offset:0x80
	v_mfma_f32_32x32x16_bf16 v[16:31], v[88:91], v[104:107], v[16:31]
	ds_read_b128 v[88:91], v215 offset:0x2080
	s_waitcnt lgkmcnt(4)
	v_mfma_f32_32x32x16_bf16 v[32:47], v[92:95], v[108:111], v[32:47]
	ds_read_b128 v[92:95], v217 offset:0x80
	v_mfma_f32_32x32x16_bf16 v[16:31], v[144:147], v[108:111], v[16:31]
	ds_read_b128 v[144:147], v217 offset:0x2080
	s_waitcnt lgkmcnt(4)
	v_mfma_f32_32x32x16_bf16 v[32:47], v[70:73], v[112:115], v[32:47]
	ds_read_b128 v[70:73], v219 offset:0x80
	v_mfma_f32_32x32x16_bf16 v[16:31], v[80:83], v[112:115], v[16:31]
	ds_read_b128 v[80:83], v219 offset:0x2080
	s_waitcnt lgkmcnt(4)
	v_mfma_f32_32x32x16_bf16 v[32:47], v[84:87], v[116:119], v[32:47]
	ds_read_b128 v[84:87], v214 offset:0
	v_mfma_f32_32x32x16_bf16 v[16:31], v[88:91], v[116:119], v[16:31]
	ds_read_b128 v[88:91], v214 offset:0x1000
	s_waitcnt lgkmcnt(4)
	v_mfma_f32_32x32x16_bf16 v[32:47], v[92:95], v[120:123], v[32:47]
	ds_read_b128 v[92:95], v216 offset:0
	v_mfma_f32_32x32x16_bf16 v[16:31], v[144:147], v[120:123], v[16:31]
	ds_read_b128 v[144:147], v216 offset:0x1000
	s_waitcnt lgkmcnt(4)
	v_mfma_f32_32x32x16_bf16 v[32:47], v[70:73], v[124:127], v[32:47]
	ds_read_b128 v[70:73], v218 offset:0
	v_mfma_f32_32x32x16_bf16 v[16:31], v[80:83], v[124:127], v[16:31]
	ds_read_b128 v[80:83], v218 offset:0x1000
	s_waitcnt lgkmcnt(4)
	v_mfma_f32_32x32x16_bf16 v[32:47], v[84:87], v[128:131], v[32:47]
	ds_read_b128 v[84:87], v220 offset:0
	v_mfma_f32_32x32x16_bf16 v[16:31], v[88:91], v[128:131], v[16:31]
	ds_read_b128 v[88:91], v220 offset:0x1000
	s_waitcnt lgkmcnt(4)
	v_mfma_f32_32x32x16_bf16 v[32:47], v[92:95], v[136:139], v[32:47]
	s_waitcnt lgkmcnt(2)
	v_mfma_f32_32x32x16_bf16 v[16:31], v[144:147], v[136:139], v[16:31]
	v_mfma_f32_32x32x16_bf16 v[32:47], v[70:73], v[132:135], v[32:47]
	s_waitcnt lgkmcnt(0)
	v_mfma_f32_32x32x16_bf16 v[16:31], v[80:83], v[132:135], v[16:31]
	v_mfma_f32_32x32x16_bf16 v[32:47], v[84:87], v[140:143], v[32:47]
	s_barrier
	v_lshl_add_u32 v222, v203, 2, s23
	s_mov_b32 s45, 0
	s_mov_b32 s44, 0
	s_nop 7
	v_max_f32_e32 v70, v33, v33
	v_max_f32_e32 v71, v32, v32
	v_mfma_f32_32x32x16_bf16 v[16:31], v[88:91], v[140:143], v[16:31]
	v_max_f32_e32 v70, v71, v70
	v_max3_f32 v70, v70, v34, v35
	v_max3_f32 v70, v70, v36, v37
	v_max3_f32 v70, v70, v38, v39
	v_max3_f32 v70, v70, v40, v41
	v_max3_f32 v70, v70, v42, v43
	v_max3_f32 v70, v70, v44, v45
	v_max3_f32 v70, v70, v46, v47
	s_nop 3
	v_max3_f32 v70, v70, v16, v17
	v_max3_f32 v70, v70, v18, v19
	v_max3_f32 v70, v70, v20, v21
	v_max3_f32 v70, v70, v22, v23
	v_max3_f32 v70, v70, v24, v25
	v_max3_f32 v70, v70, v26, v27
	v_max3_f32 v70, v70, v28, v29
	v_max3_f32 v70, v70, v30, v31
	v_mov_b32_e32 v71, v70
	s_nop 1
	v_permlane32_swap_b32_e32 v70, v71
	v_max_f32_e32 v71, v71, v71
	v_max_f32_e32 v70, v70, v70
	v_max_f32_e32 v70, v70, v71
	v_add_f32_e32 v71, 0x46ea6000, v70
	v_cmp_ge_f32_e32 vcc, s1, v71
	s_cmp_eq_u64 vcc, exec
	s_cselect_b64 vcc, -1, 0
	v_max_f32_e32 v70, 0xc6ea6000, v70
	v_cndmask_b32_e32 v221, v70, v193, vcc
	v_mul_f32_e32 v71, 0xbdd53b94, v221
	v_fmamk_f32 v32, v32, 0x3dd53b94, v71
	v_fmamk_f32 v33, v33, 0x3dd53b94, v71
	v_fmamk_f32 v34, v34, 0x3dd53b94, v71
	v_fmamk_f32 v35, v35, 0x3dd53b94, v71
	v_fmamk_f32 v36, v36, 0x3dd53b94, v71
	v_fmamk_f32 v37, v37, 0x3dd53b94, v71
	v_fmamk_f32 v38, v38, 0x3dd53b94, v71
	v_fmamk_f32 v39, v39, 0x3dd53b94, v71
	v_fmamk_f32 v40, v40, 0x3dd53b94, v71
	v_fmamk_f32 v41, v41, 0x3dd53b94, v71
	v_fmamk_f32 v42, v42, 0x3dd53b94, v71
; #define SBAR() __builtin_amdgcn_sched_barrier(0)
; #define SLOAD(k0) SLOADX(sg, k0)
; #define KADDR(slot) do { _Pragma("unroll") for (int i = 0; i < 4; ++i) { ka[i] = kb_[i] + (slot) * SHM_K; kra[i] = krb_[i] + (slot) * SHM_KR; } } while (0)
; __device__ __forceinline__ void finishSM(f32x16& p0, f32x16& p1, float alpha, float& l_reg, bf16x8& pa0, bf16x8& pa1, bf16x8& pa2, bf16x8& pa3) {
; #pragma unroll
;     for (int r = 0; r < 16; ++r) p1[r] = __builtin_amdgcn_exp2f(p1[r]);
;     float ps = 0;
; #pragma unroll
;     for (int r = 0; r < 16; ++r) ps += p0[r];
; #pragma unroll
;     for (int r = 0; r < 16; ++r) ps += p1[r];
;     { auto rr = __builtin_amdgcn_permlane32_swap(__float_as_uint(ps), __float_as_uint(ps), false, false);
;       ps = __uint_as_float(rr[0]) + __uint_as_float(rr[1]); }
;     l_reg = l_reg * alpha + ps;
;     ...
;     PK4(p0, 0, pa0); PK4(p0, 8, pa1); PK4(p1, 0, pa2); PK4(p1, 8, pa3);
; template <int MODE> ...
;     ...
;     if (2 < NT) { asm volatile("s_waitcnt vmcnt(0)" ::: "memory"); SWRITEX(sg, 2, 2); } if (3 < NT) SLOAD(3 * 64);
;     __syncthreads();
;     int ks = 1, vp = 0, kw = 0, vw = 3;
;     for (int j = 1; j < NT; ++j) {
;         KADDR(ks); SBAR();
;         if constexpr (MODE != 0) { const bool ap = ACT(j - 1), ac = ACT(j); VFr fa; if (ap) vread<0>(fa, vb0 + vp * SHM_V); if (ac) qkt<MODE>(p0, p1, ka, kra, qr); if (ap) pv_pipe(o, vb0 + vp * SHM_V, fa, pa0, pa1, pa2, pa3); }
;         else { qkt<MODE>(p0, p1, ka, kra, qr); pv_d0(o, vb0 + vp * SHM_V, pa0, pa1, pa2, pa3); }
	v_fmamk_f32 v43, v43, 0x3dd53b94, v71
	v_fmamk_f32 v44, v44, 0x3dd53b94, v71
	v_fmamk_f32 v45, v45, 0x3dd53b94, v71
	v_fmamk_f32 v46, v46, 0x3dd53b94, v71
	v_fmamk_f32 v47, v47, 0x3dd53b94, v71
	v_fmamk_f32 v16, v16, 0x3dd53b94, v71
	v_fmamk_f32 v17, v17, 0x3dd53b94, v71
	v_fmamk_f32 v18, v18, 0x3dd53b94, v71
	v_fmamk_f32 v19, v19, 0x3dd53b94, v71
	v_fmamk_f32 v20, v20, 0x3dd53b94, v71
	v_fmamk_f32 v21, v21, 0x3dd53b94, v71
	v_fmamk_f32 v22, v22, 0x3dd53b94, v71
	v_fmamk_f32 v23, v23, 0x3dd53b94, v71
	v_fmamk_f32 v24, v24, 0x3dd53b94, v71
	v_fmamk_f32 v25, v25, 0x3dd53b94, v71
	v_fmamk_f32 v26, v26, 0x3dd53b94, v71
	v_fmamk_f32 v27, v27, 0x3dd53b94, v71
	v_fmamk_f32 v28, v28, 0x3dd53b94, v71
	v_fmamk_f32 v29, v29, 0x3dd53b94, v71
	v_fmamk_f32 v30, v30, 0x3dd53b94, v71
	v_fmac_f32_e32 v71, 0x3dd53b94, v31
	v_exp_f32_e32 v31, v32
	v_exp_f32_e32 v32, v33
	v_exp_f32_e32 v33, v34
	v_exp_f32_e32 v34, v35
	v_exp_f32_e32 v35, v36
	v_exp_f32_e32 v36, v37
	v_exp_f32_e32 v37, v38
	v_exp_f32_e32 v38, v39
	v_exp_f32_e32 v39, v40
	v_exp_f32_e32 v40, v41
	v_exp_f32_e32 v41, v42
	v_exp_f32_e32 v42, v43
	v_exp_f32_e32 v43, v44
	v_exp_f32_e32 v44, v45
	v_exp_f32_e32 v45, v46
	v_exp_f32_e32 v46, v47
	v_exp_f32_e32 v47, v71
	v_add_f32_e32 v71, 0, v31
	v_add_f32_e32 v71, v32, v71
	v_add_f32_e32 v71, v33, v71
	v_add_f32_e32 v71, v34, v71
	v_add_f32_e32 v71, v35, v71
	v_add_f32_e32 v71, v36, v71
	v_add_f32_e32 v71, v37, v71
	v_add_f32_e32 v71, v38, v71
	v_add_f32_e32 v71, v39, v71
	v_add_f32_e32 v71, v40, v71
	v_add_f32_e32 v71, v41, v71
	v_add_f32_e32 v71, v42, v71
	v_exp_f32_e32 v16, v16
	v_add_f32_e32 v71, v43, v71
	v_add_f32_e32 v71, v44, v71
	v_exp_f32_e32 v17, v17
	v_add_f32_e32 v71, v45, v71
	v_exp_f32_e32 v18, v18
	v_add_f32_e32 v71, v46, v71
	s_add_i32 s0, 0, 0x18000
	v_exp_f32_e32 v19, v19
	v_add_f32_e32 v71, v16, v71
	v_cvt_pk_bf16_f32 v164, v31, v32
	v_cvt_pk_bf16_f32 v165, v33, v34
	v_cvt_pk_bf16_f32 v166, v35, v36
	v_cvt_pk_bf16_f32 v167, v37, v38
	v_cvt_pk_bf16_f32 v168, v39, v40
	v_cvt_pk_bf16_f32 v169, v41, v42
	v_cvt_pk_bf16_f32 v170, v43, v44
	v_cvt_pk_bf16_f32 v171, v45, v46
	v_cvt_pk_bf16_f32 v172, v16, v17
	v_add_u32_e32 v16, s0, v207
	v_exp_f32_e32 v20, v20
	v_exp_f32_e32 v21, v21
	v_exp_f32_e32 v22, v22
	v_exp_f32_e32 v23, v23
	v_exp_f32_e32 v24, v24
	v_exp_f32_e32 v25, v25
	v_exp_f32_e32 v26, v26
	v_exp_f32_e32 v27, v27
	v_exp_f32_e32 v28, v28
	v_exp_f32_e32 v29, v29
	v_exp_f32_e32 v30, v30
	v_cvt_pk_bf16_f32 v173, v18, v19
	v_cvt_pk_bf16_f32 v174, v20, v21
	v_cvt_pk_bf16_f32 v175, v22, v23
	v_cvt_pk_bf16_f32 v176, v24, v25
	v_cvt_pk_bf16_f32 v177, v26, v27
	v_cvt_pk_bf16_f32 v178, v28, v29
	v_cvt_pk_bf16_f32 v179, v30, v47
	s_waitcnt vmcnt(0)
	s_waitcnt vmcnt(4)
	ds_write_b128 v74, v[48:51] offset:32768
	s_waitcnt vmcnt(3)
	ds_write_b128 v75, v[60:63] offset:32768
	s_waitcnt vmcnt(2)
	ds_write_b128 v16, v[52:55]
	v_add_u32_e32 v16, s0, v208
	v_add_f32_e32 v71, v17, v71
	s_waitcnt vmcnt(1)
	ds_write_b128 v16, v[56:59]
	v_add_u32_e32 v16, 0x20000, v78
	v_add_f32_e32 v71, v18, v71
	s_waitcnt vmcnt(0)
	ds_write_b128 v16, v[64:67]
	v_lshlrev_b64 v[16:17], 1, v[68:69]
	s_and_b64 s[4:5], s[8:9], exec
	v_add_f32_e32 v71, v19, v71
	v_lshl_add_u64 v[18:19], s[6:7], 0, v[16:17]
	s_movk_i32 s0, 0x6000
	s_cselect_b32 s4, s84, 0x180000
	v_add_co_u32_e64 v18, s[6:7], s0, v18
	s_add_u32 s4, s18, s4
	v_add_f32_e32 v71, v20, v71
	v_addc_co_u32_e64 v19, s[6:7], 0, v19, s[6:7]
	s_addc_u32 s5, s19, 0
	v_add_f32_e32 v71, v21, v71
	global_load_dwordx4 v[144:147], v[18:19], off
	v_lshl_add_u64 v[18:19], v[182:183], 1, s[4:5]
	v_lshl_add_u64 v[20:21], v[180:181], 1, s[4:5]
	global_load_dwordx4 v[148:151], v[18:19], off
	global_load_dwordx4 v[152:155], v[20:21], off
	global_load_dwordx4 v[160:163], v[18:19], off offset:256
	global_load_dwordx4 v[156:159], v[20:21], off offset:256
	v_add_f32_e32 v71, v22, v71
	v_add_f32_e32 v71, v23, v71
	v_add_f32_e32 v71, v24, v71
	v_add_f32_e32 v71, v25, v71
	v_add_f32_e32 v71, v26, v71
	v_add_f32_e32 v71, v27, v71
	v_sub_f32_e32 v19, 0xc6ea6000, v70
	v_add_f32_e32 v71, v28, v71
	v_mul_f32_e32 v19, 0x3dd53b94, v19
	v_add_f32_e32 v71, v29, v71
	v_exp_f32_e32 v19, v19
	v_add_f32_e32 v71, v30, v71
	v_add_f32_e32 v71, v47, v71
	s_and_b64 s[4:5], s[8:9], exec
	v_mov_b32_e32 v72, v71
	s_cselect_b32 s33, 10, 12
	s_add_i32 s40, s39, -1
	v_permlane32_swap_b32_e32 v71, v72
	v_mul_f32_e32 v19, 0, v19
	s_add_u32 s4, s34, s20
	v_add_f32_e32 v18, v71, v72
	v_cndmask_b32_e64 v19, v19, 0, vcc
	s_addc_u32 s5, s35, s21
	v_add_f32_e32 v223, v18, v19
	v_lshl_add_u64 v[184:185], s[4:5], 0, v[16:17]
	v_mov_b64_e32 v[62:63], v[14:15]
	v_mov_b64_e32 v[46:47], v[14:15]
	v_mov_b64_e32 v[30:31], v[14:15]
	v_permlane32_swap_b32_e32 v164, v166
	v_permlane32_swap_b32_e32 v165, v167
	v_permlane32_swap_b32_e32 v168, v170
	v_permlane32_swap_b32_e32 v169, v171
	v_permlane32_swap_b32_e32 v172, v174
	v_permlane32_swap_b32_e32 v173, v175
	v_permlane32_swap_b32_e32 v176, v178
	v_permlane32_swap_b32_e32 v177, v179
	s_mov_b32 s0, 0
	v_cmp_gt_u32_e64 s[6:7], 32, v210
	s_mov_b64 s[20:21], 0x100
	v_mov_b64_e32 v[60:61], v[12:13]
	v_mov_b64_e32 v[58:59], v[10:11]
	v_mov_b64_e32 v[56:57], v[8:9]
	v_mov_b64_e32 v[54:55], v[6:7]
	v_mov_b64_e32 v[52:53], v[4:5]
	v_mov_b64_e32 v[50:51], v[2:3]
	v_mov_b64_e32 v[48:49], v[0:1]
	v_mov_b64_e32 v[44:45], v[12:13]
	v_mov_b64_e32 v[42:43], v[10:11]
	v_mov_b64_e32 v[40:41], v[8:9]
	v_mov_b64_e32 v[38:39], v[6:7]
	v_mov_b64_e32 v[36:37], v[4:5]
	v_mov_b64_e32 v[34:35], v[2:3]
	v_mov_b64_e32 v[32:33], v[0:1]
	v_mov_b64_e32 v[28:29], v[12:13]
	v_mov_b64_e32 v[26:27], v[10:11]
	v_mov_b64_e32 v[24:25], v[8:9]
	v_mov_b64_e32 v[22:23], v[6:7]
	v_mov_b64_e32 v[20:21], v[4:5]
	v_mov_b64_e32 v[18:19], v[2:3]
	v_mov_b64_e32 v[16:17], v[0:1]
	s_lshl_b32 s4, s43, 14
	s_lshl_b32 s5, s43, 13
	v_add_u32_e32 v248, s4, v213
	v_add_u32_e32 v249, s5, v214
	v_add_u32_e32 v250, s4, v215
	v_add_u32_e32 v251, s5, v216
	v_add_u32_e32 v252, s4, v217
	v_add_u32_e32 v253, s5, v218
	v_add_u32_e32 v188, s4, v219
	v_add_u32_e32 v191, s5, v220
	ds_read_b128 v[192:195], v248 offset:0x0
	ds_read_b128 v[196:199], v248 offset:0x2000
	ds_read_b128 v[224:227], v250 offset:0x0
	ds_read_b128 v[228:231], v250 offset:0x2000
	ds_read_b128 v[232:235], v252 offset:0x0
	ds_read_b128 v[236:239], v252 offset:0x2000
	ds_read_b128 v[240:243], v188 offset:0x0
	ds_read_b128 v[244:247], v188 offset:0x2000
	s_waitcnt lgkmcnt(8)
	v_readfirstlane_b32 s4, v201
	s_nop 3
	s_lshr_b32 s4, s4, 6
	s_cmp_ge_u32 s4, 4
	s_cbranch_scc1 .Lprio_m0
	s_setprio 1
; #define SBAR() __builtin_amdgcn_sched_barrier(0)
; #define KRD(dst, addr, off) asm volatile("ds_read_b128 %0, %1 offset:%2" : "=&v"(dst) : "v"(addr), "i"(off) : "memory")
; template <int MODE>
; __device__ __forceinline__ void qkt(f32x16& p0, f32x16& p1, const int (&ka)[4], const int (&kra)[4], const bf16x8* qr) {
;     ...
;     if constexpr (MODE == 0) {
;         KRD(kb0[0], ka[0], 0); KRD(kb1[0], ka[0], 8192); KRD(kb0[1], ka[1], 0); KRD(kb1[1], ka[1], 8192);
;         KRD(kb0[2], ka[2], 0); KRD(kb1[2], ka[2], 8192); asm volatile("s_waitcnt lgkmcnt(4)" ::: "memory"); SBAR(); p0 = __builtin_amdgcn_mfma_f32_32x32x16_bf16(kb0[0], qr[0], zz, 0, 0, 0); p1 = __builtin_amdgcn_mfma_f32_32x32x16_bf16(kb1[0], qr[0], zz, 0, 0, 0);
;         KRD(kb0[0], ka[3], 0); KRD(kb1[0], ka[3], 8192); asm volatile("s_waitcnt lgkmcnt(4)" ::: "memory"); SBAR(); p0 = __builtin_amdgcn_mfma_f32_32x32x16_bf16(kb0[1], qr[1], p0, 0, 0, 0); p1 = __builtin_amdgcn_mfma_f32_32x32x16_bf16(kb1[1], qr[1], p1, 0, 0, 0);
;         KRD(kb0[1], ka[0], 128); KRD(kb1[1], ka[0], 8320); asm volatile("s_waitcnt lgkmcnt(4)" ::: "memory"); SBAR(); p0 = __builtin_amdgcn_mfma_f32_32x32x16_bf16(kb0[2], qr[2], p0, 0, 0, 0); p1 = __builtin_amdgcn_mfma_f32_32x32x16_bf16(kb1[2], qr[2], p1, 0, 0, 0);
;         KRD(kb0[2], ka[1], 128); KRD(kb1[2], ka[1], 8320); asm volatile("s_waitcnt lgkmcnt(4)" ::: "memory"); SBAR(); p0 = __builtin_amdgcn_mfma_f32_32x32x16_bf16(kb0[0], qr[3], p0, 0, 0, 0); p1 = __builtin_amdgcn_mfma_f32_32x32x16_bf16(kb1[0], qr[3], p1, 0, 0, 0);
;         KRD(kb0[0], ka[2], 128); KRD(kb1[0], ka[2], 8320); asm volatile("s_waitcnt lgkmcnt(4)" ::: "memory"); SBAR(); p0 = __builtin_amdgcn_mfma_f32_32x32x16_bf16(kb0[1], qr[4], p0, 0, 0, 0); p1 = __builtin_amdgcn_mfma_f32_32x32x16_bf16(kb1[1], qr[4], p1, 0, 0, 0);
;         KRD(kb0[1], ka[3], 128); KRD(kb1[1], ka[3], 8320); asm volatile("s_waitcnt lgkmcnt(4)" ::: "memory"); SBAR(); p0 = __builtin_amdgcn_mfma_f32_32x32x16_bf16(kb0[2], qr[5], p0, 0, 0, 0); p1 = __builtin_amdgcn_mfma_f32_32x32x16_bf16(kb1[2], qr[5], p1, 0, 0, 0);
;         KRD(kb0[2], kra[0], 0); KRD(kb1[2], kra[0], 4096); asm volatile("s_waitcnt lgkmcnt(4)" ::: "memory"); SBAR(); p0 = __builtin_amdgcn_mfma_f32_32x32x16_bf16(kb0[0], qr[6], p0, 0, 0, 0); p1 = __builtin_amdgcn_mfma_f32_32x32x16_bf16(kb1[0], qr[6], p1, 0, 0, 0);
.Lprio_m0:
	s_barrier
.LBB0_286:
	s_waitcnt lgkmcnt(6)
	v_mfma_f32_32x32x16_bf16 v[80:95], v[192:195], v[96:99], 0
	ds_read_b128 v[192:195], v248 offset:0x80
	v_mfma_f32_32x32x16_bf16 v[64:79], v[196:199], v[96:99], 0
	ds_read_b128 v[196:199], v248 offset:0x2080
	s_waitcnt lgkmcnt(6)
	v_mfma_f32_32x32x16_bf16 v[80:95], v[224:227], v[100:103], v[80:95]
	ds_read_b128 v[224:227], v250 offset:0x80
	v_mfma_f32_32x32x16_bf16 v[64:79], v[228:231], v[100:103], v[64:79]
	ds_read_b128 v[228:231], v250 offset:0x2080
	s_waitcnt lgkmcnt(6)
	v_mfma_f32_32x32x16_bf16 v[80:95], v[232:235], v[104:107], v[80:95]
	ds_read_b128 v[232:235], v252 offset:0x80
	v_mfma_f32_32x32x16_bf16 v[64:79], v[236:239], v[104:107], v[64:79]
	ds_read_b128 v[236:239], v252 offset:0x2080
	s_waitcnt lgkmcnt(6)
	v_mfma_f32_32x32x16_bf16 v[80:95], v[240:243], v[108:111], v[80:95]
	ds_read_b128 v[240:243], v188 offset:0x80
	v_mfma_f32_32x32x16_bf16 v[64:79], v[244:247], v[108:111], v[64:79]
	ds_read_b128 v[244:247], v188 offset:0x2080
	s_waitcnt lgkmcnt(6)
	v_mfma_f32_32x32x16_bf16 v[80:95], v[192:195], v[112:115], v[80:95]
	ds_read_b128 v[192:195], v249 offset:0x0
	v_mfma_f32_32x32x16_bf16 v[64:79], v[196:199], v[112:115], v[64:79]
	ds_read_b128 v[196:199], v249 offset:0x1000
	s_waitcnt lgkmcnt(6)
	v_mfma_f32_32x32x16_bf16 v[80:95], v[224:227], v[116:119], v[80:95]
	ds_read_b128 v[224:227], v251 offset:0x0
	v_mfma_f32_32x32x16_bf16 v[64:79], v[228:231], v[116:119], v[64:79]
	ds_read_b128 v[228:231], v251 offset:0x1000
	s_waitcnt lgkmcnt(6)
	v_mfma_f32_32x32x16_bf16 v[80:95], v[232:235], v[120:123], v[80:95]
	ds_read_b128 v[232:235], v253 offset:0x0
	v_mfma_f32_32x32x16_bf16 v[64:79], v[236:239], v[120:123], v[64:79]
	ds_read_b128 v[236:239], v253 offset:0x1000
	s_waitcnt lgkmcnt(6)
	v_mfma_f32_32x32x16_bf16 v[80:95], v[240:243], v[124:127], v[80:95]
	ds_read_b128 v[240:243], v191 offset:0x0
	v_mfma_f32_32x32x16_bf16 v[64:79], v[244:247], v[124:127], v[64:79]
	ds_read_b128 v[244:247], v191 offset:0x1000
	v_lshl_add_u32 v200, s44, 14, v212
	s_waitcnt lgkmcnt(6)
	v_mfma_f32_32x32x16_bf16 v[80:95], v[192:195], v[128:131], v[80:95]
	ds_read_b64_tr_b16 v[192:193], v200 offset:0x0
	ds_read_b64_tr_b16 v[194:195], v200 offset:0x800
	v_mfma_f32_32x32x16_bf16 v[64:79], v[196:199], v[128:131], v[64:79]
	ds_read_b64_tr_b16 v[196:197], v200 offset:0x1000
	ds_read_b64_tr_b16 v[198:199], v200 offset:0x1800
	s_waitcnt lgkmcnt(8)
	v_mfma_f32_32x32x16_bf16 v[80:95], v[224:227], v[136:139], v[80:95]
	ds_read_b64_tr_b16 v[224:225], v200 offset:0x2000
	ds_read_b64_tr_b16 v[226:227], v200 offset:0x2800
	v_mfma_f32_32x32x16_bf16 v[64:79], v[228:231], v[136:139], v[64:79]
	ds_read_b64_tr_b16 v[228:229], v200 offset:0x3000
	ds_read_b64_tr_b16 v[230:231], v200 offset:0x3800
	s_waitcnt lgkmcnt(10)
	v_mfma_f32_32x32x16_bf16 v[80:95], v[232:235], v[132:135], v[80:95]
	ds_read_b64_tr_b16 v[232:233], v200 offset:0x200
	ds_read_b64_tr_b16 v[234:235], v200 offset:0xa00
	v_mfma_f32_32x32x16_bf16 v[64:79], v[236:239], v[132:135], v[64:79]
	ds_read_b64_tr_b16 v[236:237], v200 offset:0x1200
	ds_read_b64_tr_b16 v[238:239], v200 offset:0x1a00
	s_waitcnt lgkmcnt(12)
	v_mfma_f32_32x32x16_bf16 v[80:95], v[240:243], v[140:143], v[80:95]
	ds_read_b64_tr_b16 v[240:241], v200 offset:0x2200
	ds_read_b64_tr_b16 v[242:243], v200 offset:0x2a00
	v_mfma_f32_32x32x16_bf16 v[64:79], v[244:247], v[140:143], v[64:79]
	s_waitcnt lgkmcnt(12)
	v_mfma_f32_32x32x16_bf16 v[0:15], v[164:167], v[192:195], v[0:15]
	ds_read_b64_tr_b16 v[244:245], v200 offset:0x3200
	ds_read_b64_tr_b16 v[246:247], v200 offset:0x3a00
	s_waitcnt lgkmcnt(12)
	v_mfma_f32_32x32x16_bf16 v[0:15], v[168:171], v[196:199], v[0:15]
	ds_read_b64_tr_b16 v[192:193], v200 offset:0x400
	ds_read_b64_tr_b16 v[194:195], v200 offset:0xc00
	s_waitcnt lgkmcnt(12)
	v_mfma_f32_32x32x16_bf16 v[0:15], v[172:175], v[224:227], v[0:15]
	ds_read_b64_tr_b16 v[196:197], v200 offset:0x1400
	ds_read_b64_tr_b16 v[198:199], v200 offset:0x1c00
	s_waitcnt lgkmcnt(12)
	v_mfma_f32_32x32x16_bf16 v[0:15], v[176:179], v[228:231], v[0:15]
	ds_read_b64_tr_b16 v[224:225], v200 offset:0x2400
	ds_read_b64_tr_b16 v[226:227], v200 offset:0x2c00
	s_waitcnt lgkmcnt(12)
	v_mfma_f32_32x32x16_bf16 v[48:63], v[164:167], v[232:235], v[48:63]
	ds_read_b64_tr_b16 v[228:229], v200 offset:0x3400
	ds_read_b64_tr_b16 v[230:231], v200 offset:0x3c00
	s_waitcnt lgkmcnt(12)
	v_mfma_f32_32x32x16_bf16 v[48:63], v[168:171], v[236:239], v[48:63]
	ds_read_b64_tr_b16 v[232:233], v200 offset:0x600
	ds_read_b64_tr_b16 v[234:235], v200 offset:0xe00
	v_max_f32_e32 v248, v81, v81
	v_max_f32_e32 v250, v80, v80
	v_max_f32_e32 v248, v250, v248
	s_waitcnt lgkmcnt(12)
	v_mfma_f32_32x32x16_bf16 v[48:63], v[172:175], v[240:243], v[48:63]
	ds_read_b64_tr_b16 v[236:237], v200 offset:0x1600
	ds_read_b64_tr_b16 v[238:239], v200 offset:0x1e00
	v_max3_f32 v248, v248, v82, v83
	v_max3_f32 v248, v248, v84, v85
	v_max3_f32 v248, v248, v86, v87
	s_waitcnt lgkmcnt(12)
	v_mfma_f32_32x32x16_bf16 v[48:63], v[176:179], v[244:247], v[48:63]
	ds_read_b64_tr_b16 v[240:241], v200 offset:0x2600
	ds_read_b64_tr_b16 v[242:243], v200 offset:0x2e00
	v_max3_f32 v248, v248, v88, v89
	v_max3_f32 v248, v248, v90, v91
	v_max3_f32 v248, v248, v92, v93
	s_waitcnt lgkmcnt(12)
	v_mfma_f32_32x32x16_bf16 v[32:47], v[164:167], v[192:195], v[32:47]
	ds_read_b64_tr_b16 v[244:245], v200 offset:0x3600
	ds_read_b64_tr_b16 v[246:247], v200 offset:0x3e00
	v_max3_f32 v248, v248, v94, v95
	v_max3_f32 v248, v248, v64, v65
	v_max3_f32 v248, v248, v66, v67
	s_waitcnt lgkmcnt(12)
	v_mfma_f32_32x32x16_bf16 v[32:47], v[168:171], v[196:199], v[32:47]
	v_max3_f32 v248, v248, v68, v69
	v_max3_f32 v248, v248, v70, v71
	v_max3_f32 v248, v248, v72, v73
	s_waitcnt lgkmcnt(10)
	v_mfma_f32_32x32x16_bf16 v[32:47], v[172:175], v[224:227], v[32:47]
	v_max3_f32 v248, v248, v74, v75
	v_max3_f32 v248, v248, v76, v77
	v_max3_f32 v248, v248, v78, v79
	s_waitcnt lgkmcnt(8)
	v_mfma_f32_32x32x16_bf16 v[32:47], v[176:179], v[228:231], v[32:47]
	s_waitcnt lgkmcnt(6)
	v_mfma_f32_32x32x16_bf16 v[16:31], v[164:167], v[232:235], v[16:31]
	s_waitcnt lgkmcnt(4)
	v_mfma_f32_32x32x16_bf16 v[16:31], v[168:171], v[236:239], v[16:31]
	v_mov_b32_e32 v164, v248
	v_mov_b32_e32 v165, v248
	s_nop 1
	v_permlane32_swap_b32_e32 v164, v165
	v_max_f32_e32 v165, v165, v165
	v_max_f32_e32 v164, v164, v164
	s_waitcnt lgkmcnt(2)
	v_mfma_f32_32x32x16_bf16 v[16:31], v[172:175], v[240:243], v[16:31]
	v_max_f32_e32 v164, v164, v165
	v_sub_f32_e32 v165, v164, v221
	v_cmp_ge_f32_e32 vcc, s1, v165
	v_max_f32_e32 v165, v221, v221
	v_max_f32_e32 v164, v165, v164
	v_sub_f32_e32 v165, v221, v164
	s_waitcnt lgkmcnt(0)
	v_mfma_f32_32x32x16_bf16 v[16:31], v[176:179], v[244:247], v[16:31]
	v_mul_f32_e32 v165, 0x3dd53b94, v165
	v_exp_f32_e32 v165, v165
	s_cmp_eq_u64 vcc, exec
	s_cselect_b64 s[8:9], -1, 0
	v_cndmask_b32_e64 v224, v165, 1.0, s[8:9]
	v_cmp_gt_f32_e32 vcc, 1.0, v224
	s_barrier
; #define RESC(a) do { if (__any((a) < 1.f)) { if (hi == 0) al_l[r32] = (a); asm volatile("s_waitcnt lgkmcnt(0)" ::: "memory"); \
;     _Pragma("unroll") for (int d = 0; d < 4; ++d) _Pragma("unroll") for (int r = 0; r < 16; ++r) o[d][r] *= al_l[crow(r, hi)]; } } while (0)
; template <int MODE> ...
;     ...
;         if (ACT(j)) { partialSM<MODE>(p0, p1, m_reg, mn, al, REL0(j), hi, NEEDM(j)); RESC(al); finishSM(p0, p1, al, l_reg, pa0, pa1, pa2, pa3); }
	s_cbranch_vccz .LBB0_290
	s_and_saveexec_b64 s[4:5], s[6:7]
	ds_write_b32 v222, v224 offset:128
	s_or_b64 exec, exec, s[4:5]
	s_waitcnt lgkmcnt(0)
	v_add_u32_e32 v165, s23, v211
	ds_read_b128 v[166:169], v165 offset:224
	ds_read_b128 v[170:173], v165 offset:192
	ds_read_b128 v[174:177], v165 offset:160
	ds_read_b128 v[226:229], v165 offset:128
	s_waitcnt lgkmcnt(3)
	v_pk_mul_f32 v[12:13], v[12:13], v[166:167]
	s_waitcnt lgkmcnt(2)
	v_pk_mul_f32 v[8:9], v[8:9], v[170:171]
	s_waitcnt lgkmcnt(1)
	v_pk_mul_f32 v[4:5], v[4:5], v[174:175]
	v_pk_mul_f32 v[14:15], v[14:15], v[168:169]
	v_pk_mul_f32 v[10:11], v[10:11], v[172:173]
	v_pk_mul_f32 v[6:7], v[6:7], v[176:177]
	s_waitcnt lgkmcnt(0)
	v_pk_mul_f32 v[2:3], v[2:3], v[228:229]
	v_pk_mul_f32 v[0:1], v[0:1], v[226:227]
	v_pk_mul_f32 v[60:61], v[60:61], v[166:167]
	v_pk_mul_f32 v[56:57], v[56:57], v[170:171]
	v_pk_mul_f32 v[52:53], v[52:53], v[174:175]
	v_pk_mul_f32 v[62:63], v[62:63], v[168:169]
	v_pk_mul_f32 v[58:59], v[58:59], v[172:173]
	v_pk_mul_f32 v[54:55], v[54:55], v[176:177]
	v_pk_mul_f32 v[50:51], v[50:51], v[228:229]
	v_pk_mul_f32 v[48:49], v[48:49], v[226:227]
	v_pk_mul_f32 v[44:45], v[44:45], v[166:167]
	v_pk_mul_f32 v[40:41], v[40:41], v[170:171]
	v_pk_mul_f32 v[36:37], v[36:37], v[174:175]
	v_pk_mul_f32 v[46:47], v[46:47], v[168:169]
	v_pk_mul_f32 v[42:43], v[42:43], v[172:173]
	v_pk_mul_f32 v[38:39], v[38:39], v[176:177]
	v_pk_mul_f32 v[34:35], v[34:35], v[228:229]
	v_pk_mul_f32 v[32:33], v[32:33], v[226:227]
	v_pk_mul_f32 v[28:29], v[28:29], v[166:167]
	v_pk_mul_f32 v[24:25], v[24:25], v[170:171]
	v_pk_mul_f32 v[20:21], v[20:21], v[174:175]
	v_pk_mul_f32 v[30:31], v[30:31], v[168:169]
	v_pk_mul_f32 v[26:27], v[26:27], v[172:173]
	v_pk_mul_f32 v[22:23], v[22:23], v[176:177]
	v_pk_mul_f32 v[18:19], v[18:19], v[228:229]
	v_pk_mul_f32 v[16:17], v[16:17], v[226:227]

; #define SBAR() __builtin_amdgcn_sched_barrier(0)
; template <int D0> __device__ __forceinline__ void pv_one(f32x16& od, int vb, bf16x8 pa0, bf16x8 pa1, bf16x8 pa2, bf16x8 pa3) {
;     const s16x4 l0 = tr_read<v_rd_off(D0, 0, 0)>(vb), h0 = tr_read<v_rd_off(D0, 0, 1)>(vb), l1 = tr_read<v_rd_off(D0, 1, 0)>(vb), h1 = tr_read<v_rd_off(D0, 1, 1)>(vb);
;     const s16x4 l2 = tr_read<v_rd_off(D0, 2, 0)>(vb), h2 = tr_read<v_rd_off(D0, 2, 1)>(vb), l3 = tr_read<v_rd_off(D0, 3, 0)>(vb), h3 = tr_read<v_rd_off(D0, 3, 1)>(vb);
;     asm volatile("s_waitcnt lgkmcnt(0)" ::: "memory"); SBAR();
;     ...
;     od = __builtin_amdgcn_mfma_f32_32x32x16_bf16(pa0, PK(l0, h0), od, 0, 0, 0);
;     od = __builtin_amdgcn_mfma_f32_32x32x16_bf16(pa1, PK(l1, h1), od, 0, 0, 0);
;     od = __builtin_amdgcn_mfma_f32_32x32x16_bf16(pa2, PK(l2, h2), od, 0, 0, 0);
;     od = __builtin_amdgcn_mfma_f32_32x32x16_bf16(pa3, PK(l3, h3), od, 0, 0, 0);
;     ...
; }
; __device__ __forceinline__ void pv_d0(f32x16* o, int vb, bf16x8 pa0, bf16x8 pa1, bf16x8 pa2, bf16x8 pa3) {
;     pv_one<0>(o[0], vb, pa0, pa1, pa2, pa3); pv_one<1>(o[1], vb, pa0, pa1, pa2, pa3); pv_one<2>(o[2], vb, pa0, pa1, pa2, pa3); pv_one<3>(o[3], vb, pa0, pa1, pa2, pa3);
; template <int MODE> ...
;     ...
;     if constexpr (MODE != 0) { if (ACT(NT - 1)) { VFr fa; vread<0>(fa, vb0 + vp * SHM_V); pv_pipe(o, vb0 + vp * SHM_V, fa, pa0, pa1, pa2, pa3); } } else pv_d0(o, vb0 + vp * SHM_V, pa0, pa1, pa2, pa3);
.LBB0_296:
	s_setprio 0
	v_lshl_add_u32 v65, s44, 14, v212
	ds_read_b64_tr_b16 v[66:67], v65 offset:0
	ds_read_b64_tr_b16 v[68:69], v65 offset:0x800
	ds_read_b64_tr_b16 v[70:71], v65 offset:0x1000
	ds_read_b64_tr_b16 v[72:73], v65 offset:0x1800
	ds_read_b64_tr_b16 v[74:75], v65 offset:0x2000
	ds_read_b64_tr_b16 v[76:77], v65 offset:0x2800
	ds_read_b64_tr_b16 v[78:79], v65 offset:0x3000
	ds_read_b64_tr_b16 v[80:81], v65 offset:0x3800
	s_waitcnt lgkmcnt(0)
	s_nop 0
	v_mfma_f32_32x32x16_bf16 v[0:15], v[164:167], v[66:69], v[0:15]
	ds_read_b64_tr_b16 v[66:67], v65 offset:0x200
	ds_read_b64_tr_b16 v[68:69], v65 offset:0xa00
	v_mfma_f32_32x32x16_bf16 v[0:15], v[168:171], v[70:73], v[0:15]
	ds_read_b64_tr_b16 v[70:71], v65 offset:0x1200
	ds_read_b64_tr_b16 v[72:73], v65 offset:0x1a00
	v_mfma_f32_32x32x16_bf16 v[0:15], v[172:175], v[74:77], v[0:15]
	ds_read_b64_tr_b16 v[74:75], v65 offset:0x2200
	ds_read_b64_tr_b16 v[76:77], v65 offset:0x2a00
	v_mfma_f32_32x32x16_bf16 v[0:15], v[176:179], v[78:81], v[0:15]
	ds_read_b64_tr_b16 v[78:79], v65 offset:0x3200
	ds_read_b64_tr_b16 v[80:81], v65 offset:0x3a00
	s_waitcnt lgkmcnt(0)
	v_mfma_f32_32x32x16_bf16 v[48:63], v[164:167], v[66:69], v[48:63]
	ds_read_b64_tr_b16 v[66:67], v65 offset:0x400
	ds_read_b64_tr_b16 v[68:69], v65 offset:0xc00
	v_mfma_f32_32x32x16_bf16 v[48:63], v[168:171], v[70:73], v[48:63]
	ds_read_b64_tr_b16 v[70:71], v65 offset:0x1400
	ds_read_b64_tr_b16 v[72:73], v65 offset:0x1c00
	v_mfma_f32_32x32x16_bf16 v[48:63], v[172:175], v[74:77], v[48:63]
	ds_read_b64_tr_b16 v[74:75], v65 offset:0x2400
	ds_read_b64_tr_b16 v[76:77], v65 offset:0x2c00
	v_mfma_f32_32x32x16_bf16 v[48:63], v[176:179], v[78:81], v[48:63]
	ds_read_b64_tr_b16 v[78:79], v65 offset:0x3400
	ds_read_b64_tr_b16 v[80:81], v65 offset:0x3c00
	s_waitcnt lgkmcnt(0)
	v_mfma_f32_32x32x16_bf16 v[32:47], v[164:167], v[66:69], v[32:47]
	ds_read_b64_tr_b16 v[66:67], v65 offset:0x600
	ds_read_b64_tr_b16 v[68:69], v65 offset:0xe00
	v_mfma_f32_32x32x16_bf16 v[32:47], v[168:171], v[70:73], v[32:47]
	ds_read_b64_tr_b16 v[70:71], v65 offset:0x1600
	ds_read_b64_tr_b16 v[72:73], v65 offset:0x1e00
	v_mfma_f32_32x32x16_bf16 v[32:47], v[172:175], v[74:77], v[32:47]
	ds_read_b64_tr_b16 v[74:75], v65 offset:0x2600
	ds_read_b64_tr_b16 v[76:77], v65 offset:0x2e00
	v_mfma_f32_32x32x16_bf16 v[32:47], v[176:179], v[78:81], v[32:47]
	ds_read_b64_tr_b16 v[78:79], v65 offset:0x3600
	ds_read_b64_tr_b16 v[80:81], v65 offset:0x3e00
	s_waitcnt lgkmcnt(0)
	v_mfma_f32_32x32x16_bf16 v[16:31], v[164:167], v[66:69], v[16:31]
	s_cmp_eq_u32 s22, 0
	v_mfma_f32_32x32x16_bf16 v[16:31], v[168:171], v[70:73], v[16:31]
	v_mfma_f32_32x32x16_bf16 v[16:31], v[172:175], v[74:77], v[16:31]
	v_mfma_f32_32x32x16_bf16 v[16:31], v[176:179], v[78:81], v[16:31]
	s_cbranch_scc1 .LBB0_301
	s_and_saveexec_b64 s[4:5], s[6:7]
